# GEMM main loops: A-operand-stationary MFMA order (same weight fragment for 4 consecutive MFMAs), accumulation order unchanged
# baseline (speedup 1.0000x reference)
.LBB0_178:
	s_add_u32 s26, s22, 0xfffc0080
	s_addc_u32 s27, s23, -1
	s_add_i32 s34, 0, 0x10000
	s_cmp_eq_u32 s59, 12
	s_cselect_b32 s31, s9, s27
	s_cselect_b32 s30, s15, s26
	s_cselect_b32 s27, s13, s58
	s_cselect_b32 s26, s56, s57
	s_add_i32 s35, 0, 0x14000
	v_add_u32_e32 v140, s34, v195
	v_add_u32_e32 v166, s35, v195
	ds_read_b128 v[128:131], v140
	ds_read_b128 v[132:135], v140 offset:1024
	ds_read_b128 v[136:139], v140 offset:2048
	ds_read_b128 v[140:143], v140 offset:3072
	ds_read_b128 v[144:147], v166
	ds_read_b128 v[148:151], v166 offset:1024
	ds_read_b128 v[180:183], v166 offset:2048
	ds_read_b128 v[184:187], v166 offset:3072
	v_lshl_add_u64 v[166:167], s[22:23], 0, v[160:161]
	s_add_i32 m0, s49, 0xc000
	ds_read_b128 v[188:191], v200
	ds_read_b128 v[202:205], v200 offset:1024
	ds_read_b128 v[206:209], v200 offset:2048
	ds_read_b128 v[210:213], v200 offset:3072
	ds_read_b128 v[228:231], v200 offset:4096
	ds_read_b128 v[232:235], v200 offset:5120
	ds_read_b128 v[236:239], v200 offset:6144
	ds_read_b128 v[240:243], v200 offset:7168
	global_load_lds_dwordx4 v[166:167], off
	v_lshl_add_u64 v[166:167], s[22:23], 0, v[162:163]
	s_add_i32 m0, s49, 0xe000
	s_nop 0
	global_load_lds_dwordx4 v[166:167], off
	s_waitcnt vmcnt(8)
	s_waitcnt lgkmcnt(0)
	s_barrier
	s_setprio 1
	s_waitcnt lgkmcnt(0)
	v_mfma_f32_16x16x32_bf16 v[124:127], v[128:131], v[188:191], v[124:127]
	v_mfma_f32_16x16x32_bf16 v[112:115], v[128:131], v[206:209], v[112:115]
	v_mfma_f32_16x16x32_bf16 v[96:99], v[128:131], v[228:231], v[96:99]
	v_mfma_f32_16x16x32_bf16 v[80:83], v[128:131], v[236:239], v[80:83]
	v_mfma_f32_16x16x32_bf16 v[124:127], v[132:135], v[202:205], v[124:127]
	v_mfma_f32_16x16x32_bf16 v[112:115], v[132:135], v[210:213], v[112:115]
	v_mfma_f32_16x16x32_bf16 v[96:99], v[132:135], v[232:235], v[96:99]
	v_mfma_f32_16x16x32_bf16 v[80:83], v[132:135], v[240:243], v[80:83]
	v_mfma_f32_16x16x32_bf16 v[120:123], v[136:139], v[188:191], v[120:123]
	v_mfma_f32_16x16x32_bf16 v[104:107], v[136:139], v[206:209], v[104:107]
	v_mfma_f32_16x16x32_bf16 v[88:91], v[136:139], v[228:231], v[88:91]
	v_mfma_f32_16x16x32_bf16 v[72:75], v[136:139], v[236:239], v[72:75]
	v_mfma_f32_16x16x32_bf16 v[120:123], v[140:143], v[202:205], v[120:123]
	v_mfma_f32_16x16x32_bf16 v[104:107], v[140:143], v[210:213], v[104:107]
	v_mfma_f32_16x16x32_bf16 v[88:91], v[140:143], v[232:235], v[88:91]
	v_mfma_f32_16x16x32_bf16 v[72:75], v[140:143], v[240:243], v[72:75]
	s_setprio 0
	s_setprio 1
	v_mfma_f32_16x16x32_bf16 v[116:119], v[144:147], v[188:191], v[116:119]
	v_mfma_f32_16x16x32_bf16 v[100:103], v[144:147], v[206:209], v[100:103]
	v_mfma_f32_16x16x32_bf16 v[84:87], v[144:147], v[228:231], v[84:87]
	v_mfma_f32_16x16x32_bf16 v[68:71], v[144:147], v[236:239], v[68:71]
	v_mfma_f32_16x16x32_bf16 v[116:119], v[148:151], v[202:205], v[116:119]
	v_mfma_f32_16x16x32_bf16 v[100:103], v[148:151], v[210:213], v[100:103]
	v_mfma_f32_16x16x32_bf16 v[84:87], v[148:151], v[232:235], v[84:87]
	v_mfma_f32_16x16x32_bf16 v[68:71], v[148:151], v[240:243], v[68:71]
	v_mfma_f32_16x16x32_bf16 v[108:111], v[180:183], v[188:191], v[108:111]
	v_mfma_f32_16x16x32_bf16 v[92:95], v[180:183], v[206:209], v[92:95]
	v_mfma_f32_16x16x32_bf16 v[76:79], v[180:183], v[228:231], v[76:79]
	v_mfma_f32_16x16x32_bf16 v[64:67], v[180:183], v[236:239], v[64:67]
	v_mfma_f32_16x16x32_bf16 v[108:111], v[184:187], v[202:205], v[108:111]
	v_mfma_f32_16x16x32_bf16 v[92:95], v[184:187], v[210:213], v[92:95]
	v_mfma_f32_16x16x32_bf16 v[76:79], v[184:187], v[232:235], v[76:79]
	v_mfma_f32_16x16x32_bf16 v[64:67], v[184:187], v[240:243], v[64:67]
	s_setprio 0
	s_barrier
	s_add_i32 s34, s34, s45
	v_lshl_add_u64 v[166:167], s[26:27], 0, v[168:169]
	s_mov_b32 m0, s34
	ds_read_b128 v[188:191], v200 offset:16384
	ds_read_b128 v[202:205], v200 offset:17408
	ds_read_b128 v[206:209], v200 offset:18432
	ds_read_b128 v[210:213], v200 offset:19456
	ds_read_b128 v[228:231], v200 offset:20480
	ds_read_b128 v[232:235], v200 offset:21504
	ds_read_b128 v[236:239], v200 offset:22528
	ds_read_b128 v[240:243], v200 offset:23552
	global_load_lds_dwordx4 v[166:167], off
	s_add_i32 m0, s34, 0x2000
	s_add_u32 s36, s26, 0x40000
	v_lshl_add_u64 v[192:193], s[26:27], 0, v[152:153]
	s_addc_u32 s37, s27, 0
	s_add_i32 s34, s35, s45
	global_load_lds_dwordx4 v[192:193], off
	v_lshl_add_u64 v[198:199], s[36:37], 0, v[168:169]
	s_mov_b32 m0, s34
	v_lshl_add_u64 v[214:215], s[30:31], 0, v[154:155]
	global_load_lds_dwordx4 v[198:199], off
	v_lshl_add_u64 v[198:199], s[36:37], 0, v[152:153]
	s_add_i32 m0, s34, 0x2000
	s_nop 0
	global_load_lds_dwordx4 v[198:199], off
	v_lshl_add_u64 v[198:199], s[30:31], 0, v[156:157]
	s_mov_b32 m0, s49
	s_nop 0
	global_load_lds_dwordx4 v[198:199], off
	s_mov_b32 m0, s50
	s_nop 0
	global_load_lds_dwordx4 v[214:215], off
	s_waitcnt vmcnt(8)
	s_waitcnt lgkmcnt(0)
	s_barrier
	s_setprio 1
	s_waitcnt lgkmcnt(0)
	v_mfma_f32_16x16x32_bf16 v[60:63], v[128:131], v[188:191], v[60:63]
	v_mfma_f32_16x16x32_bf16 v[48:51], v[128:131], v[206:209], v[48:51]
	v_mfma_f32_16x16x32_bf16 v[32:35], v[128:131], v[228:231], v[32:35]
	v_mfma_f32_16x16x32_bf16 v[16:19], v[128:131], v[236:239], v[16:19]
	v_mfma_f32_16x16x32_bf16 v[60:63], v[132:135], v[202:205], v[60:63]
	v_mfma_f32_16x16x32_bf16 v[48:51], v[132:135], v[210:213], v[48:51]
	v_mfma_f32_16x16x32_bf16 v[32:35], v[132:135], v[232:235], v[32:35]
	v_mfma_f32_16x16x32_bf16 v[16:19], v[132:135], v[240:243], v[16:19]
	v_mfma_f32_16x16x32_bf16 v[56:59], v[136:139], v[188:191], v[56:59]
	v_mfma_f32_16x16x32_bf16 v[40:43], v[136:139], v[206:209], v[40:43]
	v_mfma_f32_16x16x32_bf16 v[24:27], v[136:139], v[228:231], v[24:27]
	v_mfma_f32_16x16x32_bf16 v[8:11], v[136:139], v[236:239], v[8:11]
	v_mfma_f32_16x16x32_bf16 v[56:59], v[140:143], v[202:205], v[56:59]
	v_mfma_f32_16x16x32_bf16 v[40:43], v[140:143], v[210:213], v[40:43]
	v_mfma_f32_16x16x32_bf16 v[24:27], v[140:143], v[232:235], v[24:27]
	v_mfma_f32_16x16x32_bf16 v[8:11], v[140:143], v[240:243], v[8:11]
	s_setprio 0
	s_setprio 1
	v_mfma_f32_16x16x32_bf16 v[52:55], v[144:147], v[188:191], v[52:55]
	v_mfma_f32_16x16x32_bf16 v[36:39], v[144:147], v[206:209], v[36:39]
	v_mfma_f32_16x16x32_bf16 v[20:23], v[144:147], v[228:231], v[20:23]
	v_mfma_f32_16x16x32_bf16 v[4:7], v[144:147], v[236:239], v[4:7]
	v_mfma_f32_16x16x32_bf16 v[52:55], v[148:151], v[202:205], v[52:55]
	v_mfma_f32_16x16x32_bf16 v[36:39], v[148:151], v[210:213], v[36:39]
	v_mfma_f32_16x16x32_bf16 v[20:23], v[148:151], v[232:235], v[20:23]
	v_mfma_f32_16x16x32_bf16 v[4:7], v[148:151], v[240:243], v[4:7]
	v_mfma_f32_16x16x32_bf16 v[44:47], v[180:183], v[188:191], v[44:47]
	v_mfma_f32_16x16x32_bf16 v[28:31], v[180:183], v[206:209], v[28:31]
	v_mfma_f32_16x16x32_bf16 v[12:15], v[180:183], v[228:231], v[12:15]
	v_mfma_f32_16x16x32_bf16 v[0:3], v[180:183], v[236:239], v[0:3]
	v_mfma_f32_16x16x32_bf16 v[44:47], v[184:187], v[202:205], v[44:47]
	v_mfma_f32_16x16x32_bf16 v[28:31], v[184:187], v[210:213], v[28:31]
	v_mfma_f32_16x16x32_bf16 v[12:15], v[184:187], v[232:235], v[12:15]
	v_mfma_f32_16x16x32_bf16 v[0:3], v[184:187], v[240:243], v[0:3]
	s_setprio 0
	s_barrier
	s_add_i32 s34, 0, 0x18000
	s_add_i32 s35, 0, 0x1c000
	v_add_u32_e32 v140, s34, v195
	v_add_u32_e32 v184, s35, v195
	ds_read_b128 v[128:131], v140
	ds_read_b128 v[132:135], v140 offset:1024
	ds_read_b128 v[136:139], v140 offset:2048
	ds_read_b128 v[140:143], v140 offset:3072
	ds_read_b128 v[144:147], v184
	ds_read_b128 v[148:151], v184 offset:1024
	ds_read_b128 v[180:183], v184 offset:2048
	ds_read_b128 v[184:187], v184 offset:3072
	s_add_u32 s30, s30, 0x40000
	s_addc_u32 s31, s31, 0
	s_mov_b32 m0, s51
	v_lshl_add_u64 v[244:245], s[30:31], 0, v[156:157]
	ds_read_b128 v[188:191], v200 offset:32768
	ds_read_b128 v[202:205], v200 offset:33792
	ds_read_b128 v[206:209], v200 offset:34816
	ds_read_b128 v[210:213], v200 offset:35840
	ds_read_b128 v[228:231], v200 offset:36864
	ds_read_b128 v[232:235], v200 offset:37888
	ds_read_b128 v[236:239], v200 offset:38912
	ds_read_b128 v[240:243], v200 offset:39936
	global_load_lds_dwordx4 v[244:245], off
	v_lshl_add_u64 v[244:245], s[30:31], 0, v[154:155]
	s_mov_b32 m0, s52
	s_nop 0
	global_load_lds_dwordx4 v[244:245], off
	s_waitcnt vmcnt(8)
	s_waitcnt lgkmcnt(0)
	s_barrier
	s_setprio 1
	s_waitcnt lgkmcnt(0)
	v_mfma_f32_16x16x32_bf16 v[124:127], v[128:131], v[188:191], v[124:127]
	v_mfma_f32_16x16x32_bf16 v[112:115], v[128:131], v[206:209], v[112:115]
	v_mfma_f32_16x16x32_bf16 v[96:99], v[128:131], v[228:231], v[96:99]
	v_mfma_f32_16x16x32_bf16 v[80:83], v[128:131], v[236:239], v[80:83]
	v_mfma_f32_16x16x32_bf16 v[124:127], v[132:135], v[202:205], v[124:127]
	v_mfma_f32_16x16x32_bf16 v[112:115], v[132:135], v[210:213], v[112:115]
	v_mfma_f32_16x16x32_bf16 v[96:99], v[132:135], v[232:235], v[96:99]
	v_mfma_f32_16x16x32_bf16 v[80:83], v[132:135], v[240:243], v[80:83]
	v_mfma_f32_16x16x32_bf16 v[120:123], v[136:139], v[188:191], v[120:123]
	v_mfma_f32_16x16x32_bf16 v[104:107], v[136:139], v[206:209], v[104:107]
	v_mfma_f32_16x16x32_bf16 v[88:91], v[136:139], v[228:231], v[88:91]
	v_mfma_f32_16x16x32_bf16 v[72:75], v[136:139], v[236:239], v[72:75]
	v_mfma_f32_16x16x32_bf16 v[120:123], v[140:143], v[202:205], v[120:123]
	v_mfma_f32_16x16x32_bf16 v[104:107], v[140:143], v[210:213], v[104:107]
	v_mfma_f32_16x16x32_bf16 v[88:91], v[140:143], v[232:235], v[88:91]
	v_mfma_f32_16x16x32_bf16 v[72:75], v[140:143], v[240:243], v[72:75]
	s_setprio 0
	s_setprio 1
	v_mfma_f32_16x16x32_bf16 v[116:119], v[144:147], v[188:191], v[116:119]
	v_mfma_f32_16x16x32_bf16 v[100:103], v[144:147], v[206:209], v[100:103]
	v_mfma_f32_16x16x32_bf16 v[84:87], v[144:147], v[228:231], v[84:87]
	v_mfma_f32_16x16x32_bf16 v[68:71], v[144:147], v[236:239], v[68:71]
	v_mfma_f32_16x16x32_bf16 v[116:119], v[148:151], v[202:205], v[116:119]
	v_mfma_f32_16x16x32_bf16 v[100:103], v[148:151], v[210:213], v[100:103]
	v_mfma_f32_16x16x32_bf16 v[84:87], v[148:151], v[232:235], v[84:87]
	v_mfma_f32_16x16x32_bf16 v[68:71], v[148:151], v[240:243], v[68:71]
	v_mfma_f32_16x16x32_bf16 v[108:111], v[180:183], v[188:191], v[108:111]
	v_mfma_f32_16x16x32_bf16 v[92:95], v[180:183], v[206:209], v[92:95]
	v_mfma_f32_16x16x32_bf16 v[76:79], v[180:183], v[228:231], v[76:79]
	v_mfma_f32_16x16x32_bf16 v[64:67], v[180:183], v[236:239], v[64:67]
	v_mfma_f32_16x16x32_bf16 v[108:111], v[184:187], v[202:205], v[108:111]
	v_mfma_f32_16x16x32_bf16 v[92:95], v[184:187], v[210:213], v[92:95]
	v_mfma_f32_16x16x32_bf16 v[76:79], v[184:187], v[232:235], v[76:79]
	v_mfma_f32_16x16x32_bf16 v[64:67], v[184:187], v[240:243], v[64:67]
	s_setprio 0
	s_barrier
	s_add_i32 s30, s34, s45
	v_lshl_add_u64 v[166:167], v[166:167], 0, s[20:21]
	s_mov_b32 m0, s30
	ds_read_b128 v[188:191], v200 offset:49152
	ds_read_b128 v[202:205], v200 offset:50176
	ds_read_b128 v[206:209], v200 offset:51200
	ds_read_b128 v[210:213], v200 offset:52224
	ds_read_b128 v[228:231], v200 offset:53248
	ds_read_b128 v[232:235], v200 offset:54272
	ds_read_b128 v[236:239], v200 offset:55296
	ds_read_b128 v[240:243], v200 offset:56320
	global_load_lds_dwordx4 v[166:167], off
	s_add_i32 m0, s30, 0x2000
	s_add_u32 s26, s26, 0x40080
	v_lshl_add_u64 v[166:167], v[192:193], 0, s[20:21]
	s_addc_u32 s27, s27, 0
	s_add_i32 s30, s35, s45
	global_load_lds_dwordx4 v[166:167], off
	v_lshl_add_u64 v[166:167], s[26:27], 0, v[168:169]
	s_mov_b32 m0, s30
	s_nop 0
	global_load_lds_dwordx4 v[166:167], off
	v_lshl_add_u64 v[166:167], s[26:27], 0, v[152:153]
	s_add_i32 m0, s30, 0x2000
	s_nop 0
	global_load_lds_dwordx4 v[166:167], off
	v_lshl_add_u64 v[166:167], v[198:199], 0, s[20:21]
	s_mov_b32 m0, s24
	s_nop 0
	global_load_lds_dwordx4 v[166:167], off
	v_lshl_add_u64 v[166:167], v[214:215], 0, s[20:21]
	s_mov_b32 m0, s53
	s_nop 0
	global_load_lds_dwordx4 v[166:167], off
	s_waitcnt vmcnt(8)
	s_waitcnt lgkmcnt(0)
	s_barrier
	s_setprio 1
	s_waitcnt lgkmcnt(0)
	v_mfma_f32_16x16x32_bf16 v[60:63], v[128:131], v[188:191], v[60:63]
	v_mfma_f32_16x16x32_bf16 v[48:51], v[128:131], v[206:209], v[48:51]
	v_mfma_f32_16x16x32_bf16 v[32:35], v[128:131], v[228:231], v[32:35]
	v_mfma_f32_16x16x32_bf16 v[16:19], v[128:131], v[236:239], v[16:19]
	v_mfma_f32_16x16x32_bf16 v[60:63], v[132:135], v[202:205], v[60:63]
	v_mfma_f32_16x16x32_bf16 v[48:51], v[132:135], v[210:213], v[48:51]
	v_mfma_f32_16x16x32_bf16 v[32:35], v[132:135], v[232:235], v[32:35]
	v_mfma_f32_16x16x32_bf16 v[16:19], v[132:135], v[240:243], v[16:19]
	v_mfma_f32_16x16x32_bf16 v[56:59], v[136:139], v[188:191], v[56:59]
	v_mfma_f32_16x16x32_bf16 v[40:43], v[136:139], v[206:209], v[40:43]
	v_mfma_f32_16x16x32_bf16 v[24:27], v[136:139], v[228:231], v[24:27]
	v_mfma_f32_16x16x32_bf16 v[8:11], v[136:139], v[236:239], v[8:11]
	v_mfma_f32_16x16x32_bf16 v[56:59], v[140:143], v[202:205], v[56:59]
	v_mfma_f32_16x16x32_bf16 v[40:43], v[140:143], v[210:213], v[40:43]
	v_mfma_f32_16x16x32_bf16 v[24:27], v[140:143], v[232:235], v[24:27]
	v_mfma_f32_16x16x32_bf16 v[8:11], v[140:143], v[240:243], v[8:11]
	s_setprio 0
	s_setprio 1
	v_mfma_f32_16x16x32_bf16 v[52:55], v[144:147], v[188:191], v[52:55]
	v_mfma_f32_16x16x32_bf16 v[36:39], v[144:147], v[206:209], v[36:39]
	v_mfma_f32_16x16x32_bf16 v[20:23], v[144:147], v[228:231], v[20:23]
	v_mfma_f32_16x16x32_bf16 v[4:7], v[144:147], v[236:239], v[4:7]
	v_mfma_f32_16x16x32_bf16 v[52:55], v[148:151], v[202:205], v[52:55]
	v_mfma_f32_16x16x32_bf16 v[36:39], v[148:151], v[210:213], v[36:39]
	v_mfma_f32_16x16x32_bf16 v[20:23], v[148:151], v[232:235], v[20:23]
	v_mfma_f32_16x16x32_bf16 v[4:7], v[148:151], v[240:243], v[4:7]
	v_mfma_f32_16x16x32_bf16 v[44:47], v[180:183], v[188:191], v[44:47]
	v_mfma_f32_16x16x32_bf16 v[28:31], v[180:183], v[206:209], v[28:31]
	v_mfma_f32_16x16x32_bf16 v[12:15], v[180:183], v[228:231], v[12:15]
	v_mfma_f32_16x16x32_bf16 v[0:3], v[180:183], v[236:239], v[0:3]
	v_mfma_f32_16x16x32_bf16 v[44:47], v[184:187], v[202:205], v[44:47]
	v_mfma_f32_16x16x32_bf16 v[28:31], v[184:187], v[210:213], v[28:31]
	v_mfma_f32_16x16x32_bf16 v[12:15], v[184:187], v[232:235], v[12:15]
	v_mfma_f32_16x16x32_bf16 v[0:3], v[184:187], v[240:243], v[0:3]
	s_setprio 0
	s_barrier
	s_add_i32 s59, s59, 2
	s_add_u32 s22, s22, 0x100
	s_addc_u32 s23, s23, 0
	s_add_u32 s57, s57, 0x100
	s_addc_u32 s58, s58, 0
	s_cmp_gt_u32 s59, 13
	s_cbranch_scc0 .LBB0_178
	s_and_b64 vcc, exec, s[10:11]
	s_cbranch_vccz .LBB0_181
	s_barrier

.LBB0_776:
	s_add_u32 s26, s22, 0xfffc0080
	s_addc_u32 s27, s23, -1
	s_add_i32 s36, 0, 0x10000
	s_cmp_eq_u32 s55, 12
	s_cselect_b32 s31, s15, s27
	s_cselect_b32 s30, s51, s26
	s_cselect_b32 s27, s13, s54
	s_cselect_b32 s26, s52, s53
	s_add_i32 s56, 0, 0x14000
	v_add_u32_e32 v140, s36, v204
	v_add_u32_e32 v156, s56, v204
	ds_read_b128 v[128:131], v140
	ds_read_b128 v[132:135], v140 offset:1024
	ds_read_b128 v[136:139], v140 offset:2048
	ds_read_b128 v[140:143], v140 offset:3072
	ds_read_b128 v[144:147], v156
	ds_read_b128 v[148:151], v156 offset:1024
	ds_read_b128 v[152:155], v156 offset:2048
	ds_read_b128 v[156:159], v156 offset:3072
	v_lshl_add_u64 v[202:203], s[22:23], 0, v[166:167]
	s_add_i32 m0, s42, 0xc000
	ds_read_b128 v[182:185], v206
	ds_read_b128 v[186:189], v206 offset:1024
	ds_read_b128 v[190:193], v206 offset:2048
	ds_read_b128 v[194:197], v206 offset:3072
	ds_read_b128 v[198:201], v206 offset:4096
	ds_read_b128 v[208:211], v206 offset:5120
	ds_read_b128 v[212:215], v206 offset:6144
	ds_read_b128 v[228:231], v206 offset:7168
	global_load_lds_dwordx4 v[202:203], off
	v_lshl_add_u64 v[202:203], s[22:23], 0, v[180:181]
	s_add_i32 m0, s42, 0xe000
	s_nop 0
	global_load_lds_dwordx4 v[202:203], off
	s_waitcnt vmcnt(8)
	s_waitcnt lgkmcnt(0)
	s_barrier
	s_setprio 1
	s_waitcnt lgkmcnt(0)
	v_mfma_f32_16x16x32_bf16 v[124:127], v[128:131], v[182:185], v[124:127]
	v_mfma_f32_16x16x32_bf16 v[108:111], v[128:131], v[190:193], v[108:111]
	v_mfma_f32_16x16x32_bf16 v[92:95], v[128:131], v[198:201], v[92:95]
	v_mfma_f32_16x16x32_bf16 v[76:79], v[128:131], v[212:215], v[76:79]
	v_mfma_f32_16x16x32_bf16 v[124:127], v[132:135], v[186:189], v[124:127]
	v_mfma_f32_16x16x32_bf16 v[108:111], v[132:135], v[194:197], v[108:111]
	v_mfma_f32_16x16x32_bf16 v[92:95], v[132:135], v[208:211], v[92:95]
	v_mfma_f32_16x16x32_bf16 v[76:79], v[132:135], v[228:231], v[76:79]
	v_mfma_f32_16x16x32_bf16 v[120:123], v[136:139], v[182:185], v[120:123]
	v_mfma_f32_16x16x32_bf16 v[104:107], v[136:139], v[190:193], v[104:107]
	v_mfma_f32_16x16x32_bf16 v[88:91], v[136:139], v[198:201], v[88:91]
	v_mfma_f32_16x16x32_bf16 v[72:75], v[136:139], v[212:215], v[72:75]
	v_mfma_f32_16x16x32_bf16 v[120:123], v[140:143], v[186:189], v[120:123]
	v_mfma_f32_16x16x32_bf16 v[104:107], v[140:143], v[194:197], v[104:107]
	v_mfma_f32_16x16x32_bf16 v[88:91], v[140:143], v[208:211], v[88:91]
	v_mfma_f32_16x16x32_bf16 v[72:75], v[140:143], v[228:231], v[72:75]
	s_setprio 0
	s_setprio 1
	v_mfma_f32_16x16x32_bf16 v[116:119], v[144:147], v[182:185], v[116:119]
	v_mfma_f32_16x16x32_bf16 v[100:103], v[144:147], v[190:193], v[100:103]
	v_mfma_f32_16x16x32_bf16 v[84:87], v[144:147], v[198:201], v[84:87]
	v_mfma_f32_16x16x32_bf16 v[68:71], v[144:147], v[212:215], v[68:71]
	v_mfma_f32_16x16x32_bf16 v[116:119], v[148:151], v[186:189], v[116:119]
	v_mfma_f32_16x16x32_bf16 v[100:103], v[148:151], v[194:197], v[100:103]
	v_mfma_f32_16x16x32_bf16 v[84:87], v[148:151], v[208:211], v[84:87]
	v_mfma_f32_16x16x32_bf16 v[68:71], v[148:151], v[228:231], v[68:71]
	v_mfma_f32_16x16x32_bf16 v[112:115], v[152:155], v[182:185], v[112:115]
	v_mfma_f32_16x16x32_bf16 v[96:99], v[152:155], v[190:193], v[96:99]
	v_mfma_f32_16x16x32_bf16 v[80:83], v[152:155], v[198:201], v[80:83]
	v_mfma_f32_16x16x32_bf16 v[64:67], v[152:155], v[212:215], v[64:67]
	v_mfma_f32_16x16x32_bf16 v[112:115], v[156:159], v[186:189], v[112:115]
	v_mfma_f32_16x16x32_bf16 v[96:99], v[156:159], v[194:197], v[96:99]
	v_mfma_f32_16x16x32_bf16 v[80:83], v[156:159], v[208:211], v[80:83]
	v_mfma_f32_16x16x32_bf16 v[64:67], v[156:159], v[228:231], v[64:67]
	s_setprio 0
	s_barrier
	s_add_i32 s36, s36, s35
	v_lshl_add_u64 v[202:203], s[26:27], 0, v[168:169]
	s_mov_b32 m0, s36
	ds_read_b128 v[182:185], v206 offset:16384
	ds_read_b128 v[186:189], v206 offset:17408
	ds_read_b128 v[190:193], v206 offset:18432
	ds_read_b128 v[194:197], v206 offset:19456
	ds_read_b128 v[198:201], v206 offset:20480
	ds_read_b128 v[208:211], v206 offset:21504
	ds_read_b128 v[212:215], v206 offset:22528
	ds_read_b128 v[228:231], v206 offset:23552
	global_load_lds_dwordx4 v[202:203], off
	s_add_i32 m0, s36, 0x2000
	s_add_u32 s36, s26, 0x40000
	v_lshl_add_u64 v[232:233], s[26:27], 0, v[160:161]
	s_addc_u32 s37, s27, 0
	s_add_i32 s56, s56, s35
	global_load_lds_dwordx4 v[232:233], off
	v_lshl_add_u64 v[234:235], s[36:37], 0, v[168:169]
	s_mov_b32 m0, s56
	v_lshl_add_u64 v[236:237], s[30:31], 0, v[162:163]
	global_load_lds_dwordx4 v[234:235], off
	v_lshl_add_u64 v[234:235], s[36:37], 0, v[160:161]
	s_add_i32 m0, s56, 0x2000
	s_nop 0
	global_load_lds_dwordx4 v[234:235], off
	v_lshl_add_u64 v[234:235], s[30:31], 0, v[164:165]
	s_mov_b32 m0, s42
	s_nop 0
	global_load_lds_dwordx4 v[234:235], off
	s_mov_b32 m0, s43
	s_nop 0
	global_load_lds_dwordx4 v[236:237], off
	s_waitcnt vmcnt(8)
	s_waitcnt lgkmcnt(0)
	s_barrier
	s_setprio 1
	s_waitcnt lgkmcnt(0)
	v_mfma_f32_16x16x32_bf16 v[60:63], v[128:131], v[182:185], v[60:63]
	v_mfma_f32_16x16x32_bf16 v[44:47], v[128:131], v[190:193], v[44:47]
	v_mfma_f32_16x16x32_bf16 v[28:31], v[128:131], v[198:201], v[28:31]
	v_mfma_f32_16x16x32_bf16 v[12:15], v[128:131], v[212:215], v[12:15]
	v_mfma_f32_16x16x32_bf16 v[60:63], v[132:135], v[186:189], v[60:63]
	v_mfma_f32_16x16x32_bf16 v[44:47], v[132:135], v[194:197], v[44:47]
	v_mfma_f32_16x16x32_bf16 v[28:31], v[132:135], v[208:211], v[28:31]
	v_mfma_f32_16x16x32_bf16 v[12:15], v[132:135], v[228:231], v[12:15]
	v_mfma_f32_16x16x32_bf16 v[56:59], v[136:139], v[182:185], v[56:59]
	v_mfma_f32_16x16x32_bf16 v[40:43], v[136:139], v[190:193], v[40:43]
	v_mfma_f32_16x16x32_bf16 v[24:27], v[136:139], v[198:201], v[24:27]
	v_mfma_f32_16x16x32_bf16 v[8:11], v[136:139], v[212:215], v[8:11]
	v_mfma_f32_16x16x32_bf16 v[56:59], v[140:143], v[186:189], v[56:59]
	v_mfma_f32_16x16x32_bf16 v[40:43], v[140:143], v[194:197], v[40:43]
	v_mfma_f32_16x16x32_bf16 v[24:27], v[140:143], v[208:211], v[24:27]
	v_mfma_f32_16x16x32_bf16 v[8:11], v[140:143], v[228:231], v[8:11]
	s_setprio 0
	s_setprio 1
	v_mfma_f32_16x16x32_bf16 v[52:55], v[144:147], v[182:185], v[52:55]
	v_mfma_f32_16x16x32_bf16 v[36:39], v[144:147], v[190:193], v[36:39]
	v_mfma_f32_16x16x32_bf16 v[20:23], v[144:147], v[198:201], v[20:23]
	v_mfma_f32_16x16x32_bf16 v[4:7], v[144:147], v[212:215], v[4:7]
	v_mfma_f32_16x16x32_bf16 v[52:55], v[148:151], v[186:189], v[52:55]
	v_mfma_f32_16x16x32_bf16 v[36:39], v[148:151], v[194:197], v[36:39]
	v_mfma_f32_16x16x32_bf16 v[20:23], v[148:151], v[208:211], v[20:23]
	v_mfma_f32_16x16x32_bf16 v[4:7], v[148:151], v[228:231], v[4:7]
	v_mfma_f32_16x16x32_bf16 v[48:51], v[152:155], v[182:185], v[48:51]
	v_mfma_f32_16x16x32_bf16 v[32:35], v[152:155], v[190:193], v[32:35]
	v_mfma_f32_16x16x32_bf16 v[16:19], v[152:155], v[198:201], v[16:19]
	v_mfma_f32_16x16x32_bf16 v[0:3], v[152:155], v[212:215], v[0:3]
	v_mfma_f32_16x16x32_bf16 v[48:51], v[156:159], v[186:189], v[48:51]
	v_mfma_f32_16x16x32_bf16 v[32:35], v[156:159], v[194:197], v[32:35]
	v_mfma_f32_16x16x32_bf16 v[16:19], v[156:159], v[208:211], v[16:19]
	v_mfma_f32_16x16x32_bf16 v[0:3], v[156:159], v[228:231], v[0:3]
	s_setprio 0
	s_barrier
	s_add_i32 s36, 0, 0x18000
	s_add_i32 s37, 0, 0x1c000
	v_add_u32_e32 v140, s36, v204
	v_add_u32_e32 v156, s37, v204
	ds_read_b128 v[128:131], v140
	ds_read_b128 v[132:135], v140 offset:1024
	ds_read_b128 v[136:139], v140 offset:2048
	ds_read_b128 v[140:143], v140 offset:3072
	ds_read_b128 v[144:147], v156
	ds_read_b128 v[148:151], v156 offset:1024
	ds_read_b128 v[152:155], v156 offset:2048
	ds_read_b128 v[156:159], v156 offset:3072
	s_add_u32 s30, s30, 0x40000
	s_addc_u32 s31, s31, 0
	s_mov_b32 m0, s44
	v_lshl_add_u64 v[238:239], s[30:31], 0, v[164:165]
	ds_read_b128 v[182:185], v206 offset:32768
	ds_read_b128 v[186:189], v206 offset:33792
	ds_read_b128 v[190:193], v206 offset:34816
	ds_read_b128 v[194:197], v206 offset:35840
	ds_read_b128 v[198:201], v206 offset:36864
	ds_read_b128 v[208:211], v206 offset:37888
	ds_read_b128 v[212:215], v206 offset:38912
	ds_read_b128 v[228:231], v206 offset:39936
	global_load_lds_dwordx4 v[238:239], off
	v_lshl_add_u64 v[238:239], s[30:31], 0, v[162:163]
	s_mov_b32 m0, s45
	s_nop 0
	global_load_lds_dwordx4 v[238:239], off
	s_waitcnt vmcnt(8)
	s_waitcnt lgkmcnt(0)
	s_barrier
	s_setprio 1
	s_waitcnt lgkmcnt(0)
	v_mfma_f32_16x16x32_bf16 v[124:127], v[128:131], v[182:185], v[124:127]
	v_mfma_f32_16x16x32_bf16 v[108:111], v[128:131], v[190:193], v[108:111]
	v_mfma_f32_16x16x32_bf16 v[92:95], v[128:131], v[198:201], v[92:95]
	v_mfma_f32_16x16x32_bf16 v[76:79], v[128:131], v[212:215], v[76:79]
	v_mfma_f32_16x16x32_bf16 v[124:127], v[132:135], v[186:189], v[124:127]
	v_mfma_f32_16x16x32_bf16 v[108:111], v[132:135], v[194:197], v[108:111]
	v_mfma_f32_16x16x32_bf16 v[92:95], v[132:135], v[208:211], v[92:95]
	v_mfma_f32_16x16x32_bf16 v[76:79], v[132:135], v[228:231], v[76:79]
	v_mfma_f32_16x16x32_bf16 v[120:123], v[136:139], v[182:185], v[120:123]
	v_mfma_f32_16x16x32_bf16 v[104:107], v[136:139], v[190:193], v[104:107]
	v_mfma_f32_16x16x32_bf16 v[88:91], v[136:139], v[198:201], v[88:91]
	v_mfma_f32_16x16x32_bf16 v[72:75], v[136:139], v[212:215], v[72:75]
	v_mfma_f32_16x16x32_bf16 v[120:123], v[140:143], v[186:189], v[120:123]
	v_mfma_f32_16x16x32_bf16 v[104:107], v[140:143], v[194:197], v[104:107]
	v_mfma_f32_16x16x32_bf16 v[88:91], v[140:143], v[208:211], v[88:91]
	v_mfma_f32_16x16x32_bf16 v[72:75], v[140:143], v[228:231], v[72:75]
	s_setprio 0
	s_setprio 1
	v_mfma_f32_16x16x32_bf16 v[116:119], v[144:147], v[182:185], v[116:119]
	v_mfma_f32_16x16x32_bf16 v[100:103], v[144:147], v[190:193], v[100:103]
	v_mfma_f32_16x16x32_bf16 v[84:87], v[144:147], v[198:201], v[84:87]
	v_mfma_f32_16x16x32_bf16 v[68:71], v[144:147], v[212:215], v[68:71]
	v_mfma_f32_16x16x32_bf16 v[116:119], v[148:151], v[186:189], v[116:119]
	v_mfma_f32_16x16x32_bf16 v[100:103], v[148:151], v[194:197], v[100:103]
	v_mfma_f32_16x16x32_bf16 v[84:87], v[148:151], v[208:211], v[84:87]
	v_mfma_f32_16x16x32_bf16 v[68:71], v[148:151], v[228:231], v[68:71]
	v_mfma_f32_16x16x32_bf16 v[112:115], v[152:155], v[182:185], v[112:115]
	v_mfma_f32_16x16x32_bf16 v[96:99], v[152:155], v[190:193], v[96:99]
	v_mfma_f32_16x16x32_bf16 v[80:83], v[152:155], v[198:201], v[80:83]
	v_mfma_f32_16x16x32_bf16 v[64:67], v[152:155], v[212:215], v[64:67]
	v_mfma_f32_16x16x32_bf16 v[112:115], v[156:159], v[186:189], v[112:115]
	v_mfma_f32_16x16x32_bf16 v[96:99], v[156:159], v[194:197], v[96:99]
	v_mfma_f32_16x16x32_bf16 v[80:83], v[156:159], v[208:211], v[80:83]
	v_mfma_f32_16x16x32_bf16 v[64:67], v[156:159], v[228:231], v[64:67]
	s_setprio 0
	s_barrier
	s_add_i32 s30, s36, s35
	v_lshl_add_u64 v[202:203], v[202:203], 0, s[20:21]
	s_mov_b32 m0, s30
	ds_read_b128 v[182:185], v206 offset:49152
	ds_read_b128 v[186:189], v206 offset:50176
	ds_read_b128 v[190:193], v206 offset:51200
	ds_read_b128 v[194:197], v206 offset:52224
	ds_read_b128 v[198:201], v206 offset:53248
	ds_read_b128 v[208:211], v206 offset:54272
	ds_read_b128 v[212:215], v206 offset:55296
	ds_read_b128 v[228:231], v206 offset:56320
	global_load_lds_dwordx4 v[202:203], off
	s_add_i32 m0, s30, 0x2000
	s_add_u32 s26, s26, 0x40080
	v_lshl_add_u64 v[202:203], v[232:233], 0, s[20:21]
	s_addc_u32 s27, s27, 0
	s_add_i32 s30, s37, s35
	global_load_lds_dwordx4 v[202:203], off
	v_lshl_add_u64 v[202:203], s[26:27], 0, v[168:169]
	s_mov_b32 m0, s30
	s_nop 0
	global_load_lds_dwordx4 v[202:203], off
	v_lshl_add_u64 v[202:203], s[26:27], 0, v[160:161]
	s_add_i32 m0, s30, 0x2000
	s_nop 0
	global_load_lds_dwordx4 v[202:203], off
	v_lshl_add_u64 v[202:203], v[234:235], 0, s[20:21]
	s_mov_b32 m0, s47
	s_nop 0
	global_load_lds_dwordx4 v[202:203], off
	v_lshl_add_u64 v[202:203], v[236:237], 0, s[20:21]
	s_mov_b32 m0, s48
	s_nop 0
	global_load_lds_dwordx4 v[202:203], off
	s_waitcnt vmcnt(8)
	s_waitcnt lgkmcnt(0)
	s_barrier
	s_setprio 1
	s_waitcnt lgkmcnt(0)
	v_mfma_f32_16x16x32_bf16 v[60:63], v[128:131], v[182:185], v[60:63]
	v_mfma_f32_16x16x32_bf16 v[44:47], v[128:131], v[190:193], v[44:47]
	v_mfma_f32_16x16x32_bf16 v[28:31], v[128:131], v[198:201], v[28:31]
	v_mfma_f32_16x16x32_bf16 v[12:15], v[128:131], v[212:215], v[12:15]
	v_mfma_f32_16x16x32_bf16 v[60:63], v[132:135], v[186:189], v[60:63]
	v_mfma_f32_16x16x32_bf16 v[44:47], v[132:135], v[194:197], v[44:47]
	v_mfma_f32_16x16x32_bf16 v[28:31], v[132:135], v[208:211], v[28:31]
	v_mfma_f32_16x16x32_bf16 v[12:15], v[132:135], v[228:231], v[12:15]
	v_mfma_f32_16x16x32_bf16 v[56:59], v[136:139], v[182:185], v[56:59]
	v_mfma_f32_16x16x32_bf16 v[40:43], v[136:139], v[190:193], v[40:43]
	v_mfma_f32_16x16x32_bf16 v[24:27], v[136:139], v[198:201], v[24:27]
	v_mfma_f32_16x16x32_bf16 v[8:11], v[136:139], v[212:215], v[8:11]
	v_mfma_f32_16x16x32_bf16 v[56:59], v[140:143], v[186:189], v[56:59]
	v_mfma_f32_16x16x32_bf16 v[40:43], v[140:143], v[194:197], v[40:43]
	v_mfma_f32_16x16x32_bf16 v[24:27], v[140:143], v[208:211], v[24:27]
	v_mfma_f32_16x16x32_bf16 v[8:11], v[140:143], v[228:231], v[8:11]
	s_setprio 0
	s_setprio 1
	v_mfma_f32_16x16x32_bf16 v[52:55], v[144:147], v[182:185], v[52:55]
	v_mfma_f32_16x16x32_bf16 v[36:39], v[144:147], v[190:193], v[36:39]
	v_mfma_f32_16x16x32_bf16 v[20:23], v[144:147], v[198:201], v[20:23]
	v_mfma_f32_16x16x32_bf16 v[4:7], v[144:147], v[212:215], v[4:7]
	v_mfma_f32_16x16x32_bf16 v[52:55], v[148:151], v[186:189], v[52:55]
	v_mfma_f32_16x16x32_bf16 v[36:39], v[148:151], v[194:197], v[36:39]
	v_mfma_f32_16x16x32_bf16 v[20:23], v[148:151], v[208:211], v[20:23]
	v_mfma_f32_16x16x32_bf16 v[4:7], v[148:151], v[228:231], v[4:7]
	v_mfma_f32_16x16x32_bf16 v[48:51], v[152:155], v[182:185], v[48:51]
	v_mfma_f32_16x16x32_bf16 v[32:35], v[152:155], v[190:193], v[32:35]
	v_mfma_f32_16x16x32_bf16 v[16:19], v[152:155], v[198:201], v[16:19]
	v_mfma_f32_16x16x32_bf16 v[0:3], v[152:155], v[212:215], v[0:3]
	v_mfma_f32_16x16x32_bf16 v[48:51], v[156:159], v[186:189], v[48:51]
	v_mfma_f32_16x16x32_bf16 v[32:35], v[156:159], v[194:197], v[32:35]
	v_mfma_f32_16x16x32_bf16 v[16:19], v[156:159], v[208:211], v[16:19]
	v_mfma_f32_16x16x32_bf16 v[0:3], v[156:159], v[228:231], v[0:3]
	s_setprio 0
	s_barrier
	s_add_i32 s55, s55, 2
	s_add_u32 s22, s22, 0x100
	s_addc_u32 s23, s23, 0
	s_add_u32 s53, s53, 0x100
	s_addc_u32 s54, s54, 0
	s_cmp_gt_u32 s55, 13
	s_cbranch_scc0 .LBB0_776
	s_and_b64 vcc, exec, s[10:11]
	s_cbranch_vccz .LBB0_779
	s_barrier

.LBB0_890:
	s_add_u32 s18, s0, 0xfffc0080
	s_addc_u32 s19, s1, -1
	s_add_i32 s36, 0, 0x10000
	s_cmp_eq_u32 s50, 12
	s_cselect_b32 s23, s13, s19
	s_cselect_b32 s22, s46, s18
	s_cselect_b32 s19, s11, s49
	s_cselect_b32 s18, s47, s48
	s_add_i32 s51, 0, 0x14000
	v_add_u32_e32 v140, s36, v193
	v_add_u32_e32 v180, s51, v193
	ds_read_b128 v[128:131], v140
	ds_read_b128 v[132:135], v140 offset:1024
	ds_read_b128 v[136:139], v140 offset:2048
	ds_read_b128 v[140:143], v140 offset:3072
	ds_read_b128 v[144:147], v180
	ds_read_b128 v[148:151], v180 offset:1024
	ds_read_b128 v[164:167], v180 offset:2048
	ds_read_b128 v[180:183], v180 offset:3072
	v_lshl_add_u64 v[196:197], s[0:1], 0, v[160:161]
	s_add_i32 m0, s30, 0xc000
	ds_read_b128 v[184:187], v198
	ds_read_b128 v[188:191], v198 offset:1024
	ds_read_b128 v[200:203], v198 offset:2048
	ds_read_b128 v[204:207], v198 offset:3072
	ds_read_b128 v[208:211], v198 offset:4096
	ds_read_b128 v[212:215], v198 offset:5120
	ds_read_b128 v[228:231], v198 offset:6144
	ds_read_b128 v[232:235], v198 offset:7168
	global_load_lds_dwordx4 v[196:197], off
	v_lshl_add_u64 v[196:197], s[0:1], 0, v[162:163]
	s_add_i32 m0, s30, 0xe000
	s_nop 0
	global_load_lds_dwordx4 v[196:197], off
	s_waitcnt vmcnt(8)
	s_waitcnt lgkmcnt(0)
	s_barrier
	s_setprio 1
	s_waitcnt lgkmcnt(0)
	v_mfma_f32_16x16x32_bf16 v[124:127], v[128:131], v[184:187], v[124:127]
	v_mfma_f32_16x16x32_bf16 v[108:111], v[128:131], v[200:203], v[108:111]
	v_mfma_f32_16x16x32_bf16 v[92:95], v[128:131], v[208:211], v[92:95]
	v_mfma_f32_16x16x32_bf16 v[76:79], v[128:131], v[228:231], v[76:79]
	v_mfma_f32_16x16x32_bf16 v[124:127], v[132:135], v[188:191], v[124:127]
	v_mfma_f32_16x16x32_bf16 v[108:111], v[132:135], v[204:207], v[108:111]
	v_mfma_f32_16x16x32_bf16 v[92:95], v[132:135], v[212:215], v[92:95]
	v_mfma_f32_16x16x32_bf16 v[76:79], v[132:135], v[232:235], v[76:79]
	v_mfma_f32_16x16x32_bf16 v[120:123], v[136:139], v[184:187], v[120:123]
	v_mfma_f32_16x16x32_bf16 v[104:107], v[136:139], v[200:203], v[104:107]
	v_mfma_f32_16x16x32_bf16 v[88:91], v[136:139], v[208:211], v[88:91]
	v_mfma_f32_16x16x32_bf16 v[72:75], v[136:139], v[228:231], v[72:75]
	v_mfma_f32_16x16x32_bf16 v[120:123], v[140:143], v[188:191], v[120:123]
	v_mfma_f32_16x16x32_bf16 v[104:107], v[140:143], v[204:207], v[104:107]
	v_mfma_f32_16x16x32_bf16 v[88:91], v[140:143], v[212:215], v[88:91]
	v_mfma_f32_16x16x32_bf16 v[72:75], v[140:143], v[232:235], v[72:75]
	s_setprio 0
	s_setprio 1
	v_mfma_f32_16x16x32_bf16 v[116:119], v[144:147], v[184:187], v[116:119]
	v_mfma_f32_16x16x32_bf16 v[100:103], v[144:147], v[200:203], v[100:103]
	v_mfma_f32_16x16x32_bf16 v[84:87], v[144:147], v[208:211], v[84:87]
	v_mfma_f32_16x16x32_bf16 v[68:71], v[144:147], v[228:231], v[68:71]
	v_mfma_f32_16x16x32_bf16 v[116:119], v[148:151], v[188:191], v[116:119]
	v_mfma_f32_16x16x32_bf16 v[100:103], v[148:151], v[204:207], v[100:103]
	v_mfma_f32_16x16x32_bf16 v[84:87], v[148:151], v[212:215], v[84:87]
	v_mfma_f32_16x16x32_bf16 v[68:71], v[148:151], v[232:235], v[68:71]
	v_mfma_f32_16x16x32_bf16 v[112:115], v[164:167], v[184:187], v[112:115]
	v_mfma_f32_16x16x32_bf16 v[96:99], v[164:167], v[200:203], v[96:99]
	v_mfma_f32_16x16x32_bf16 v[80:83], v[164:167], v[208:211], v[80:83]
	v_mfma_f32_16x16x32_bf16 v[64:67], v[164:167], v[228:231], v[64:67]
	v_mfma_f32_16x16x32_bf16 v[112:115], v[180:183], v[188:191], v[112:115]
	v_mfma_f32_16x16x32_bf16 v[96:99], v[180:183], v[204:207], v[96:99]
	v_mfma_f32_16x16x32_bf16 v[80:83], v[180:183], v[212:215], v[80:83]
	v_mfma_f32_16x16x32_bf16 v[64:67], v[180:183], v[232:235], v[64:67]
	s_setprio 0
	s_barrier
	s_add_i32 s36, s36, s27
	v_lshl_add_u64 v[196:197], s[18:19], 0, v[168:169]
	s_mov_b32 m0, s36
	ds_read_b128 v[184:187], v198 offset:16384
	ds_read_b128 v[188:191], v198 offset:17408
	ds_read_b128 v[200:203], v198 offset:18432
	ds_read_b128 v[204:207], v198 offset:19456
	ds_read_b128 v[208:211], v198 offset:20480
	ds_read_b128 v[212:215], v198 offset:21504
	ds_read_b128 v[228:231], v198 offset:22528
	ds_read_b128 v[232:235], v198 offset:23552
	global_load_lds_dwordx4 v[196:197], off
	s_add_i32 m0, s36, 0x2000
	s_add_u32 s36, s18, 0x40000
	v_lshl_add_u64 v[236:237], s[18:19], 0, v[152:153]
	s_addc_u32 s37, s19, 0
	s_add_i32 s51, s51, s27
	global_load_lds_dwordx4 v[236:237], off
	v_lshl_add_u64 v[238:239], s[36:37], 0, v[168:169]
	s_mov_b32 m0, s51
	v_lshl_add_u64 v[240:241], s[22:23], 0, v[154:155]
	global_load_lds_dwordx4 v[238:239], off
	v_lshl_add_u64 v[238:239], s[36:37], 0, v[152:153]
	s_add_i32 m0, s51, 0x2000
	s_nop 0
	global_load_lds_dwordx4 v[238:239], off
	v_lshl_add_u64 v[238:239], s[22:23], 0, v[156:157]
	s_mov_b32 m0, s30
	s_nop 0
	global_load_lds_dwordx4 v[238:239], off
	s_mov_b32 m0, s31
	s_nop 0
	global_load_lds_dwordx4 v[240:241], off
	s_waitcnt vmcnt(8)
	s_waitcnt lgkmcnt(0)
	s_barrier
	s_setprio 1
	s_waitcnt lgkmcnt(0)
	v_mfma_f32_16x16x32_bf16 v[60:63], v[128:131], v[184:187], v[60:63]
	v_mfma_f32_16x16x32_bf16 v[44:47], v[128:131], v[200:203], v[44:47]
	v_mfma_f32_16x16x32_bf16 v[28:31], v[128:131], v[208:211], v[28:31]
	v_mfma_f32_16x16x32_bf16 v[12:15], v[128:131], v[228:231], v[12:15]
	v_mfma_f32_16x16x32_bf16 v[60:63], v[132:135], v[188:191], v[60:63]
	v_mfma_f32_16x16x32_bf16 v[44:47], v[132:135], v[204:207], v[44:47]
	v_mfma_f32_16x16x32_bf16 v[28:31], v[132:135], v[212:215], v[28:31]
	v_mfma_f32_16x16x32_bf16 v[12:15], v[132:135], v[232:235], v[12:15]
	v_mfma_f32_16x16x32_bf16 v[56:59], v[136:139], v[184:187], v[56:59]
	v_mfma_f32_16x16x32_bf16 v[40:43], v[136:139], v[200:203], v[40:43]
	v_mfma_f32_16x16x32_bf16 v[24:27], v[136:139], v[208:211], v[24:27]
	v_mfma_f32_16x16x32_bf16 v[8:11], v[136:139], v[228:231], v[8:11]
	v_mfma_f32_16x16x32_bf16 v[56:59], v[140:143], v[188:191], v[56:59]
	v_mfma_f32_16x16x32_bf16 v[40:43], v[140:143], v[204:207], v[40:43]
	v_mfma_f32_16x16x32_bf16 v[24:27], v[140:143], v[212:215], v[24:27]
	v_mfma_f32_16x16x32_bf16 v[8:11], v[140:143], v[232:235], v[8:11]
	s_setprio 0
	s_setprio 1
	v_mfma_f32_16x16x32_bf16 v[52:55], v[144:147], v[184:187], v[52:55]
	v_mfma_f32_16x16x32_bf16 v[36:39], v[144:147], v[200:203], v[36:39]
	v_mfma_f32_16x16x32_bf16 v[20:23], v[144:147], v[208:211], v[20:23]
	v_mfma_f32_16x16x32_bf16 v[4:7], v[144:147], v[228:231], v[4:7]
	v_mfma_f32_16x16x32_bf16 v[52:55], v[148:151], v[188:191], v[52:55]
	v_mfma_f32_16x16x32_bf16 v[36:39], v[148:151], v[204:207], v[36:39]
	v_mfma_f32_16x16x32_bf16 v[20:23], v[148:151], v[212:215], v[20:23]
	v_mfma_f32_16x16x32_bf16 v[4:7], v[148:151], v[232:235], v[4:7]
	v_mfma_f32_16x16x32_bf16 v[48:51], v[164:167], v[184:187], v[48:51]
	v_mfma_f32_16x16x32_bf16 v[32:35], v[164:167], v[200:203], v[32:35]
	v_mfma_f32_16x16x32_bf16 v[16:19], v[164:167], v[208:211], v[16:19]
	v_mfma_f32_16x16x32_bf16 v[0:3], v[164:167], v[228:231], v[0:3]
	v_mfma_f32_16x16x32_bf16 v[48:51], v[180:183], v[188:191], v[48:51]
	v_mfma_f32_16x16x32_bf16 v[32:35], v[180:183], v[204:207], v[32:35]
	v_mfma_f32_16x16x32_bf16 v[16:19], v[180:183], v[212:215], v[16:19]
	v_mfma_f32_16x16x32_bf16 v[0:3], v[180:183], v[232:235], v[0:3]
	s_setprio 0
	s_barrier
	s_add_i32 s36, 0, 0x18000
	s_add_i32 s37, 0, 0x1c000
	v_add_u32_e32 v140, s36, v193
	v_add_u32_e32 v180, s37, v193
	ds_read_b128 v[128:131], v140
	ds_read_b128 v[132:135], v140 offset:1024
	ds_read_b128 v[136:139], v140 offset:2048
	ds_read_b128 v[140:143], v140 offset:3072
	ds_read_b128 v[144:147], v180
	ds_read_b128 v[148:151], v180 offset:1024
	ds_read_b128 v[164:167], v180 offset:2048
	ds_read_b128 v[180:183], v180 offset:3072
	s_add_u32 s22, s22, 0x40000
	s_addc_u32 s23, s23, 0
	s_mov_b32 m0, s34
	v_lshl_add_u64 v[242:243], s[22:23], 0, v[156:157]
	ds_read_b128 v[184:187], v198 offset:32768
	ds_read_b128 v[188:191], v198 offset:33792
	ds_read_b128 v[200:203], v198 offset:34816
	ds_read_b128 v[204:207], v198 offset:35840
	ds_read_b128 v[208:211], v198 offset:36864
	ds_read_b128 v[212:215], v198 offset:37888
	ds_read_b128 v[228:231], v198 offset:38912
	ds_read_b128 v[232:235], v198 offset:39936
	global_load_lds_dwordx4 v[242:243], off
	v_lshl_add_u64 v[242:243], s[22:23], 0, v[154:155]
	s_mov_b32 m0, s35
	s_nop 0
	global_load_lds_dwordx4 v[242:243], off
	s_waitcnt vmcnt(8)
	s_waitcnt lgkmcnt(0)
	s_barrier
	s_setprio 1
	s_waitcnt lgkmcnt(0)
	v_mfma_f32_16x16x32_bf16 v[124:127], v[128:131], v[184:187], v[124:127]
	v_mfma_f32_16x16x32_bf16 v[108:111], v[128:131], v[200:203], v[108:111]
	v_mfma_f32_16x16x32_bf16 v[92:95], v[128:131], v[208:211], v[92:95]
	v_mfma_f32_16x16x32_bf16 v[76:79], v[128:131], v[228:231], v[76:79]
	v_mfma_f32_16x16x32_bf16 v[124:127], v[132:135], v[188:191], v[124:127]
	v_mfma_f32_16x16x32_bf16 v[108:111], v[132:135], v[204:207], v[108:111]
	v_mfma_f32_16x16x32_bf16 v[92:95], v[132:135], v[212:215], v[92:95]
	v_mfma_f32_16x16x32_bf16 v[76:79], v[132:135], v[232:235], v[76:79]
	v_mfma_f32_16x16x32_bf16 v[120:123], v[136:139], v[184:187], v[120:123]
	v_mfma_f32_16x16x32_bf16 v[104:107], v[136:139], v[200:203], v[104:107]
	v_mfma_f32_16x16x32_bf16 v[88:91], v[136:139], v[208:211], v[88:91]
	v_mfma_f32_16x16x32_bf16 v[72:75], v[136:139], v[228:231], v[72:75]
	v_mfma_f32_16x16x32_bf16 v[120:123], v[140:143], v[188:191], v[120:123]
	v_mfma_f32_16x16x32_bf16 v[104:107], v[140:143], v[204:207], v[104:107]
	v_mfma_f32_16x16x32_bf16 v[88:91], v[140:143], v[212:215], v[88:91]
	v_mfma_f32_16x16x32_bf16 v[72:75], v[140:143], v[232:235], v[72:75]
	s_setprio 0
	s_setprio 1
	v_mfma_f32_16x16x32_bf16 v[116:119], v[144:147], v[184:187], v[116:119]
	v_mfma_f32_16x16x32_bf16 v[100:103], v[144:147], v[200:203], v[100:103]
	v_mfma_f32_16x16x32_bf16 v[84:87], v[144:147], v[208:211], v[84:87]
	v_mfma_f32_16x16x32_bf16 v[68:71], v[144:147], v[228:231], v[68:71]
	v_mfma_f32_16x16x32_bf16 v[116:119], v[148:151], v[188:191], v[116:119]
	v_mfma_f32_16x16x32_bf16 v[100:103], v[148:151], v[204:207], v[100:103]
	v_mfma_f32_16x16x32_bf16 v[84:87], v[148:151], v[212:215], v[84:87]
	v_mfma_f32_16x16x32_bf16 v[68:71], v[148:151], v[232:235], v[68:71]
	v_mfma_f32_16x16x32_bf16 v[112:115], v[164:167], v[184:187], v[112:115]
	v_mfma_f32_16x16x32_bf16 v[96:99], v[164:167], v[200:203], v[96:99]
	v_mfma_f32_16x16x32_bf16 v[80:83], v[164:167], v[208:211], v[80:83]
	v_mfma_f32_16x16x32_bf16 v[64:67], v[164:167], v[228:231], v[64:67]
	v_mfma_f32_16x16x32_bf16 v[112:115], v[180:183], v[188:191], v[112:115]
	v_mfma_f32_16x16x32_bf16 v[96:99], v[180:183], v[204:207], v[96:99]
	v_mfma_f32_16x16x32_bf16 v[80:83], v[180:183], v[212:215], v[80:83]
	v_mfma_f32_16x16x32_bf16 v[64:67], v[180:183], v[232:235], v[64:67]
	s_setprio 0
	s_barrier
	s_add_i32 s22, s36, s27
	v_lshl_add_u64 v[196:197], v[196:197], 0, s[20:21]
	s_mov_b32 m0, s22
	ds_read_b128 v[184:187], v198 offset:49152
	ds_read_b128 v[188:191], v198 offset:50176
	ds_read_b128 v[200:203], v198 offset:51200
	ds_read_b128 v[204:207], v198 offset:52224
	ds_read_b128 v[208:211], v198 offset:53248
	ds_read_b128 v[212:215], v198 offset:54272
	ds_read_b128 v[228:231], v198 offset:55296
	ds_read_b128 v[232:235], v198 offset:56320
	global_load_lds_dwordx4 v[196:197], off
	s_add_i32 m0, s22, 0x2000
	s_add_u32 s18, s18, 0x40080
	v_lshl_add_u64 v[196:197], v[236:237], 0, s[20:21]
	s_addc_u32 s19, s19, 0
	s_add_i32 s22, s37, s27
	global_load_lds_dwordx4 v[196:197], off
	v_lshl_add_u64 v[196:197], s[18:19], 0, v[168:169]
	s_mov_b32 m0, s22
	s_nop 0
	global_load_lds_dwordx4 v[196:197], off
	v_lshl_add_u64 v[196:197], s[18:19], 0, v[152:153]
	s_add_i32 m0, s22, 0x2000
	s_nop 0
	global_load_lds_dwordx4 v[196:197], off
	v_lshl_add_u64 v[196:197], v[238:239], 0, s[20:21]
	s_mov_b32 m0, s24
	s_nop 0
	global_load_lds_dwordx4 v[196:197], off
	v_lshl_add_u64 v[196:197], v[240:241], 0, s[20:21]
	s_mov_b32 m0, s42
	s_nop 0
	global_load_lds_dwordx4 v[196:197], off
	s_waitcnt vmcnt(8)
	s_waitcnt lgkmcnt(0)
	s_barrier
	s_setprio 1
	s_waitcnt lgkmcnt(0)
	v_mfma_f32_16x16x32_bf16 v[60:63], v[128:131], v[184:187], v[60:63]
	v_mfma_f32_16x16x32_bf16 v[44:47], v[128:131], v[200:203], v[44:47]
	v_mfma_f32_16x16x32_bf16 v[28:31], v[128:131], v[208:211], v[28:31]
	v_mfma_f32_16x16x32_bf16 v[12:15], v[128:131], v[228:231], v[12:15]
	v_mfma_f32_16x16x32_bf16 v[60:63], v[132:135], v[188:191], v[60:63]
	v_mfma_f32_16x16x32_bf16 v[44:47], v[132:135], v[204:207], v[44:47]
	v_mfma_f32_16x16x32_bf16 v[28:31], v[132:135], v[212:215], v[28:31]
	v_mfma_f32_16x16x32_bf16 v[12:15], v[132:135], v[232:235], v[12:15]
	v_mfma_f32_16x16x32_bf16 v[56:59], v[136:139], v[184:187], v[56:59]
	v_mfma_f32_16x16x32_bf16 v[40:43], v[136:139], v[200:203], v[40:43]
	v_mfma_f32_16x16x32_bf16 v[24:27], v[136:139], v[208:211], v[24:27]
	v_mfma_f32_16x16x32_bf16 v[8:11], v[136:139], v[228:231], v[8:11]
	v_mfma_f32_16x16x32_bf16 v[56:59], v[140:143], v[188:191], v[56:59]
	v_mfma_f32_16x16x32_bf16 v[40:43], v[140:143], v[204:207], v[40:43]
	v_mfma_f32_16x16x32_bf16 v[24:27], v[140:143], v[212:215], v[24:27]
	v_mfma_f32_16x16x32_bf16 v[8:11], v[140:143], v[232:235], v[8:11]
	s_setprio 0
	s_setprio 1
	v_mfma_f32_16x16x32_bf16 v[52:55], v[144:147], v[184:187], v[52:55]
	v_mfma_f32_16x16x32_bf16 v[36:39], v[144:147], v[200:203], v[36:39]
	v_mfma_f32_16x16x32_bf16 v[20:23], v[144:147], v[208:211], v[20:23]
	v_mfma_f32_16x16x32_bf16 v[4:7], v[144:147], v[228:231], v[4:7]
	v_mfma_f32_16x16x32_bf16 v[52:55], v[148:151], v[188:191], v[52:55]
	v_mfma_f32_16x16x32_bf16 v[36:39], v[148:151], v[204:207], v[36:39]
	v_mfma_f32_16x16x32_bf16 v[20:23], v[148:151], v[212:215], v[20:23]
	v_mfma_f32_16x16x32_bf16 v[4:7], v[148:151], v[232:235], v[4:7]
	v_mfma_f32_16x16x32_bf16 v[48:51], v[164:167], v[184:187], v[48:51]
	v_mfma_f32_16x16x32_bf16 v[32:35], v[164:167], v[200:203], v[32:35]
	v_mfma_f32_16x16x32_bf16 v[16:19], v[164:167], v[208:211], v[16:19]
	v_mfma_f32_16x16x32_bf16 v[0:3], v[164:167], v[228:231], v[0:3]
	v_mfma_f32_16x16x32_bf16 v[48:51], v[180:183], v[188:191], v[48:51]
	v_mfma_f32_16x16x32_bf16 v[32:35], v[180:183], v[204:207], v[32:35]
	v_mfma_f32_16x16x32_bf16 v[16:19], v[180:183], v[212:215], v[16:19]
	v_mfma_f32_16x16x32_bf16 v[0:3], v[180:183], v[232:235], v[0:3]
	s_setprio 0
	s_barrier
	s_add_i32 s50, s50, 2
	s_add_u32 s0, s0, 0x100
	s_addc_u32 s1, s1, 0
	s_add_u32 s48, s48, 0x100
	s_addc_u32 s49, s49, 0
	s_cmp_gt_u32 s50, 13
	s_cbranch_scc0 .LBB0_890
	s_and_b64 vcc, exec, s[8:9]
	s_cbranch_vccz .LBB0_893
	s_barrier

.LBB0_986:
	s_add_u32 s34, s8, 0xfff00080
	s_addc_u32 s35, s9, -1
	s_add_i32 s36, 0, 0x10000
	s_cmp_eq_u32 s57, 60
	s_cselect_b32 s41, s23, s35
	s_cselect_b32 s40, s53, s34
	s_cselect_b32 s35, s19, s56
	s_cselect_b32 s34, s54, s55
	s_add_i32 s58, 0, 0x14000
	v_add_u32_e32 v140, s36, v228
	v_add_u32_e32 v156, s58, v228
	ds_read_b128 v[128:131], v140
	ds_read_b128 v[132:135], v140 offset:1024
	ds_read_b128 v[136:139], v140 offset:2048
	ds_read_b128 v[140:143], v140 offset:3072
	ds_read_b128 v[144:147], v156
	ds_read_b128 v[148:151], v156 offset:1024
	ds_read_b128 v[152:155], v156 offset:2048
	ds_read_b128 v[156:159], v156 offset:3072
	v_lshl_add_u64 v[214:215], s[8:9], 0, v[186:187]
	s_add_i32 m0, s44, 0xc000
	ds_read_b128 v[160:163], v230
	ds_read_b128 v[164:167], v230 offset:1024
	ds_read_b128 v[190:193], v230 offset:2048
	ds_read_b128 v[194:197], v230 offset:3072
	ds_read_b128 v[198:201], v230 offset:4096
	ds_read_b128 v[202:205], v230 offset:5120
	ds_read_b128 v[206:209], v230 offset:6144
	ds_read_b128 v[210:213], v230 offset:7168
	global_load_lds_dwordx4 v[214:215], off
	v_lshl_add_u64 v[214:215], s[8:9], 0, v[188:189]
	s_add_i32 m0, s44, 0xe000
	s_nop 0
	global_load_lds_dwordx4 v[214:215], off
	s_waitcnt vmcnt(8)
	s_waitcnt lgkmcnt(0)
	s_barrier
	s_setprio 1
	s_waitcnt lgkmcnt(0)
	v_mfma_f32_16x16x32_bf16 v[124:127], v[128:131], v[160:163], v[124:127]
	v_mfma_f32_16x16x32_bf16 v[108:111], v[128:131], v[190:193], v[108:111]
	v_mfma_f32_16x16x32_bf16 v[92:95], v[128:131], v[198:201], v[92:95]
	v_mfma_f32_16x16x32_bf16 v[76:79], v[128:131], v[206:209], v[76:79]
	v_mfma_f32_16x16x32_bf16 v[124:127], v[132:135], v[164:167], v[124:127]
	v_mfma_f32_16x16x32_bf16 v[108:111], v[132:135], v[194:197], v[108:111]
	v_mfma_f32_16x16x32_bf16 v[92:95], v[132:135], v[202:205], v[92:95]
	v_mfma_f32_16x16x32_bf16 v[76:79], v[132:135], v[210:213], v[76:79]
	v_mfma_f32_16x16x32_bf16 v[120:123], v[136:139], v[160:163], v[120:123]
	v_mfma_f32_16x16x32_bf16 v[104:107], v[136:139], v[190:193], v[104:107]
	v_mfma_f32_16x16x32_bf16 v[88:91], v[136:139], v[198:201], v[88:91]
	v_mfma_f32_16x16x32_bf16 v[72:75], v[136:139], v[206:209], v[72:75]
	v_mfma_f32_16x16x32_bf16 v[120:123], v[140:143], v[164:167], v[120:123]
	v_mfma_f32_16x16x32_bf16 v[104:107], v[140:143], v[194:197], v[104:107]
	v_mfma_f32_16x16x32_bf16 v[88:91], v[140:143], v[202:205], v[88:91]
	v_mfma_f32_16x16x32_bf16 v[72:75], v[140:143], v[210:213], v[72:75]
	s_setprio 0
	s_setprio 1
	v_mfma_f32_16x16x32_bf16 v[116:119], v[144:147], v[160:163], v[116:119]
	v_mfma_f32_16x16x32_bf16 v[100:103], v[144:147], v[190:193], v[100:103]
	v_mfma_f32_16x16x32_bf16 v[84:87], v[144:147], v[198:201], v[84:87]
	v_mfma_f32_16x16x32_bf16 v[68:71], v[144:147], v[206:209], v[68:71]
	v_mfma_f32_16x16x32_bf16 v[116:119], v[148:151], v[164:167], v[116:119]
	v_mfma_f32_16x16x32_bf16 v[100:103], v[148:151], v[194:197], v[100:103]
	v_mfma_f32_16x16x32_bf16 v[84:87], v[148:151], v[202:205], v[84:87]
	v_mfma_f32_16x16x32_bf16 v[68:71], v[148:151], v[210:213], v[68:71]
	v_mfma_f32_16x16x32_bf16 v[112:115], v[152:155], v[160:163], v[112:115]
	v_mfma_f32_16x16x32_bf16 v[96:99], v[152:155], v[190:193], v[96:99]
	v_mfma_f32_16x16x32_bf16 v[80:83], v[152:155], v[198:201], v[80:83]
	v_mfma_f32_16x16x32_bf16 v[64:67], v[152:155], v[206:209], v[64:67]
	v_mfma_f32_16x16x32_bf16 v[112:115], v[156:159], v[164:167], v[112:115]
	v_mfma_f32_16x16x32_bf16 v[96:99], v[156:159], v[194:197], v[96:99]
	v_mfma_f32_16x16x32_bf16 v[80:83], v[156:159], v[202:205], v[80:83]
	v_mfma_f32_16x16x32_bf16 v[64:67], v[156:159], v[210:213], v[64:67]
	s_setprio 0
	s_barrier
	s_add_i32 s36, s36, s43
	v_lshl_add_u64 v[214:215], s[34:35], 0, v[168:169]
	s_mov_b32 m0, s36
	ds_read_b128 v[160:163], v230 offset:16384
	ds_read_b128 v[164:167], v230 offset:17408
	ds_read_b128 v[190:193], v230 offset:18432
	ds_read_b128 v[194:197], v230 offset:19456
	ds_read_b128 v[198:201], v230 offset:20480
	ds_read_b128 v[202:205], v230 offset:21504
	ds_read_b128 v[206:209], v230 offset:22528
	ds_read_b128 v[210:213], v230 offset:23552
	global_load_lds_dwordx4 v[214:215], off
	s_add_i32 m0, s36, 0x2000
	s_add_u32 s36, s34, 0x100000
	v_lshl_add_u64 v[232:233], s[34:35], 0, v[180:181]
	s_addc_u32 s37, s35, 0
	s_add_i32 s58, s58, s43
	global_load_lds_dwordx4 v[232:233], off
	v_lshl_add_u64 v[234:235], s[36:37], 0, v[168:169]
	s_mov_b32 m0, s58
	v_lshl_add_u64 v[236:237], s[40:41], 0, v[182:183]
	global_load_lds_dwordx4 v[234:235], off
	v_lshl_add_u64 v[234:235], s[36:37], 0, v[180:181]
	s_add_i32 m0, s58, 0x2000
	s_nop 0
	global_load_lds_dwordx4 v[234:235], off
	v_lshl_add_u64 v[234:235], s[40:41], 0, v[184:185]
	s_mov_b32 m0, s44
	s_nop 0
	global_load_lds_dwordx4 v[234:235], off
	s_mov_b32 m0, s45
	s_nop 0
	global_load_lds_dwordx4 v[236:237], off
	s_waitcnt vmcnt(8)
	s_waitcnt lgkmcnt(0)
	s_barrier
	s_setprio 1
	s_waitcnt lgkmcnt(0)
	v_mfma_f32_16x16x32_bf16 v[60:63], v[128:131], v[160:163], v[60:63]
	v_mfma_f32_16x16x32_bf16 v[44:47], v[128:131], v[190:193], v[44:47]
	v_mfma_f32_16x16x32_bf16 v[28:31], v[128:131], v[198:201], v[28:31]
	v_mfma_f32_16x16x32_bf16 v[12:15], v[128:131], v[206:209], v[12:15]
	v_mfma_f32_16x16x32_bf16 v[60:63], v[132:135], v[164:167], v[60:63]
	v_mfma_f32_16x16x32_bf16 v[44:47], v[132:135], v[194:197], v[44:47]
	v_mfma_f32_16x16x32_bf16 v[28:31], v[132:135], v[202:205], v[28:31]
	v_mfma_f32_16x16x32_bf16 v[12:15], v[132:135], v[210:213], v[12:15]
	v_mfma_f32_16x16x32_bf16 v[56:59], v[136:139], v[160:163], v[56:59]
	v_mfma_f32_16x16x32_bf16 v[40:43], v[136:139], v[190:193], v[40:43]
	v_mfma_f32_16x16x32_bf16 v[24:27], v[136:139], v[198:201], v[24:27]
	v_mfma_f32_16x16x32_bf16 v[8:11], v[136:139], v[206:209], v[8:11]
	v_mfma_f32_16x16x32_bf16 v[56:59], v[140:143], v[164:167], v[56:59]
	v_mfma_f32_16x16x32_bf16 v[40:43], v[140:143], v[194:197], v[40:43]
	v_mfma_f32_16x16x32_bf16 v[24:27], v[140:143], v[202:205], v[24:27]
	v_mfma_f32_16x16x32_bf16 v[8:11], v[140:143], v[210:213], v[8:11]
	s_setprio 0
	s_setprio 1
	v_mfma_f32_16x16x32_bf16 v[52:55], v[144:147], v[160:163], v[52:55]
	v_mfma_f32_16x16x32_bf16 v[36:39], v[144:147], v[190:193], v[36:39]
	v_mfma_f32_16x16x32_bf16 v[20:23], v[144:147], v[198:201], v[20:23]
	v_mfma_f32_16x16x32_bf16 v[4:7], v[144:147], v[206:209], v[4:7]
	v_mfma_f32_16x16x32_bf16 v[52:55], v[148:151], v[164:167], v[52:55]
	v_mfma_f32_16x16x32_bf16 v[36:39], v[148:151], v[194:197], v[36:39]
	v_mfma_f32_16x16x32_bf16 v[20:23], v[148:151], v[202:205], v[20:23]
	v_mfma_f32_16x16x32_bf16 v[4:7], v[148:151], v[210:213], v[4:7]
	v_mfma_f32_16x16x32_bf16 v[48:51], v[152:155], v[160:163], v[48:51]
	v_mfma_f32_16x16x32_bf16 v[32:35], v[152:155], v[190:193], v[32:35]
	v_mfma_f32_16x16x32_bf16 v[16:19], v[152:155], v[198:201], v[16:19]
	v_mfma_f32_16x16x32_bf16 v[0:3], v[152:155], v[206:209], v[0:3]
	v_mfma_f32_16x16x32_bf16 v[48:51], v[156:159], v[164:167], v[48:51]
	v_mfma_f32_16x16x32_bf16 v[32:35], v[156:159], v[194:197], v[32:35]
	v_mfma_f32_16x16x32_bf16 v[16:19], v[156:159], v[202:205], v[16:19]
	v_mfma_f32_16x16x32_bf16 v[0:3], v[156:159], v[210:213], v[0:3]
	s_setprio 0
	s_barrier
	s_add_i32 s58, 0, 0x18000
	s_add_i32 s59, 0, 0x1c000
	v_add_u32_e32 v140, s58, v228
	v_add_u32_e32 v156, s59, v228
	ds_read_b128 v[128:131], v140
	ds_read_b128 v[132:135], v140 offset:1024
	ds_read_b128 v[136:139], v140 offset:2048
	ds_read_b128 v[140:143], v140 offset:3072
	ds_read_b128 v[144:147], v156
	ds_read_b128 v[148:151], v156 offset:1024
	ds_read_b128 v[152:155], v156 offset:2048
	ds_read_b128 v[156:159], v156 offset:3072
	s_add_u32 s36, s40, 0x100000
	s_addc_u32 s37, s41, 0
	s_mov_b32 m0, s46
	v_lshl_add_u64 v[238:239], s[36:37], 0, v[184:185]
	ds_read_b128 v[160:163], v230 offset:32768
	ds_read_b128 v[164:167], v230 offset:33792
	ds_read_b128 v[190:193], v230 offset:34816
	ds_read_b128 v[194:197], v230 offset:35840
	ds_read_b128 v[198:201], v230 offset:36864
	ds_read_b128 v[202:205], v230 offset:37888
	ds_read_b128 v[206:209], v230 offset:38912
	ds_read_b128 v[210:213], v230 offset:39936
	global_load_lds_dwordx4 v[238:239], off
	v_lshl_add_u64 v[238:239], s[36:37], 0, v[182:183]
	s_mov_b32 m0, s47
	s_nop 0
	global_load_lds_dwordx4 v[238:239], off
	s_waitcnt vmcnt(8)
	s_waitcnt lgkmcnt(0)
	s_barrier
	s_setprio 1
	s_waitcnt lgkmcnt(0)
	v_mfma_f32_16x16x32_bf16 v[124:127], v[128:131], v[160:163], v[124:127]
	v_mfma_f32_16x16x32_bf16 v[108:111], v[128:131], v[190:193], v[108:111]
	v_mfma_f32_16x16x32_bf16 v[92:95], v[128:131], v[198:201], v[92:95]
	v_mfma_f32_16x16x32_bf16 v[76:79], v[128:131], v[206:209], v[76:79]
	v_mfma_f32_16x16x32_bf16 v[124:127], v[132:135], v[164:167], v[124:127]
	v_mfma_f32_16x16x32_bf16 v[108:111], v[132:135], v[194:197], v[108:111]
	v_mfma_f32_16x16x32_bf16 v[92:95], v[132:135], v[202:205], v[92:95]
	v_mfma_f32_16x16x32_bf16 v[76:79], v[132:135], v[210:213], v[76:79]
	v_mfma_f32_16x16x32_bf16 v[120:123], v[136:139], v[160:163], v[120:123]
	v_mfma_f32_16x16x32_bf16 v[104:107], v[136:139], v[190:193], v[104:107]
	v_mfma_f32_16x16x32_bf16 v[88:91], v[136:139], v[198:201], v[88:91]
	v_mfma_f32_16x16x32_bf16 v[72:75], v[136:139], v[206:209], v[72:75]
	v_mfma_f32_16x16x32_bf16 v[120:123], v[140:143], v[164:167], v[120:123]
	v_mfma_f32_16x16x32_bf16 v[104:107], v[140:143], v[194:197], v[104:107]
	v_mfma_f32_16x16x32_bf16 v[88:91], v[140:143], v[202:205], v[88:91]
	v_mfma_f32_16x16x32_bf16 v[72:75], v[140:143], v[210:213], v[72:75]
	s_setprio 0
	s_setprio 1
	v_mfma_f32_16x16x32_bf16 v[116:119], v[144:147], v[160:163], v[116:119]
	v_mfma_f32_16x16x32_bf16 v[100:103], v[144:147], v[190:193], v[100:103]
	v_mfma_f32_16x16x32_bf16 v[84:87], v[144:147], v[198:201], v[84:87]
	v_mfma_f32_16x16x32_bf16 v[68:71], v[144:147], v[206:209], v[68:71]
	v_mfma_f32_16x16x32_bf16 v[116:119], v[148:151], v[164:167], v[116:119]
	v_mfma_f32_16x16x32_bf16 v[100:103], v[148:151], v[194:197], v[100:103]
	v_mfma_f32_16x16x32_bf16 v[84:87], v[148:151], v[202:205], v[84:87]
	v_mfma_f32_16x16x32_bf16 v[68:71], v[148:151], v[210:213], v[68:71]
	v_mfma_f32_16x16x32_bf16 v[112:115], v[152:155], v[160:163], v[112:115]
	v_mfma_f32_16x16x32_bf16 v[96:99], v[152:155], v[190:193], v[96:99]
	v_mfma_f32_16x16x32_bf16 v[80:83], v[152:155], v[198:201], v[80:83]
	v_mfma_f32_16x16x32_bf16 v[64:67], v[152:155], v[206:209], v[64:67]
	v_mfma_f32_16x16x32_bf16 v[112:115], v[156:159], v[164:167], v[112:115]
	v_mfma_f32_16x16x32_bf16 v[96:99], v[156:159], v[194:197], v[96:99]
	v_mfma_f32_16x16x32_bf16 v[80:83], v[156:159], v[202:205], v[80:83]
	v_mfma_f32_16x16x32_bf16 v[64:67], v[156:159], v[210:213], v[64:67]
	s_setprio 0
	s_barrier
	s_add_i32 s36, s58, s43
	v_lshl_add_u64 v[214:215], v[214:215], 0, s[20:21]
	s_mov_b32 m0, s36
	ds_read_b128 v[160:163], v230 offset:49152
	ds_read_b128 v[164:167], v230 offset:50176
	ds_read_b128 v[190:193], v230 offset:51200
	ds_read_b128 v[194:197], v230 offset:52224
	ds_read_b128 v[198:201], v230 offset:53248
	ds_read_b128 v[202:205], v230 offset:54272
	ds_read_b128 v[206:209], v230 offset:55296
	ds_read_b128 v[210:213], v230 offset:56320
	global_load_lds_dwordx4 v[214:215], off
	s_add_i32 m0, s36, 0x2000
	s_add_u32 s34, s34, 0x100080
	v_lshl_add_u64 v[214:215], v[232:233], 0, s[20:21]
	s_addc_u32 s35, s35, 0
	s_add_i32 s36, s59, s43
	global_load_lds_dwordx4 v[214:215], off
	v_lshl_add_u64 v[214:215], s[34:35], 0, v[168:169]
	s_mov_b32 m0, s36
	s_nop 0
	global_load_lds_dwordx4 v[214:215], off
	v_lshl_add_u64 v[214:215], s[34:35], 0, v[180:181]
	s_add_i32 m0, s36, 0x2000
	s_nop 0
	global_load_lds_dwordx4 v[214:215], off
	v_lshl_add_u64 v[214:215], v[234:235], 0, s[20:21]
	s_mov_b32 m0, s50
	s_nop 0
	global_load_lds_dwordx4 v[214:215], off
	v_lshl_add_u64 v[214:215], v[236:237], 0, s[20:21]
	s_mov_b32 m0, s51
	s_nop 0
	global_load_lds_dwordx4 v[214:215], off
	s_waitcnt vmcnt(8)
	s_waitcnt lgkmcnt(0)
	s_barrier
	s_setprio 1
	s_waitcnt lgkmcnt(0)
	v_mfma_f32_16x16x32_bf16 v[60:63], v[128:131], v[160:163], v[60:63]
	v_mfma_f32_16x16x32_bf16 v[44:47], v[128:131], v[190:193], v[44:47]
	v_mfma_f32_16x16x32_bf16 v[28:31], v[128:131], v[198:201], v[28:31]
	v_mfma_f32_16x16x32_bf16 v[12:15], v[128:131], v[206:209], v[12:15]
	v_mfma_f32_16x16x32_bf16 v[60:63], v[132:135], v[164:167], v[60:63]
	v_mfma_f32_16x16x32_bf16 v[44:47], v[132:135], v[194:197], v[44:47]
	v_mfma_f32_16x16x32_bf16 v[28:31], v[132:135], v[202:205], v[28:31]
	v_mfma_f32_16x16x32_bf16 v[12:15], v[132:135], v[210:213], v[12:15]
	v_mfma_f32_16x16x32_bf16 v[56:59], v[136:139], v[160:163], v[56:59]
	v_mfma_f32_16x16x32_bf16 v[40:43], v[136:139], v[190:193], v[40:43]
	v_mfma_f32_16x16x32_bf16 v[24:27], v[136:139], v[198:201], v[24:27]
	v_mfma_f32_16x16x32_bf16 v[8:11], v[136:139], v[206:209], v[8:11]
	v_mfma_f32_16x16x32_bf16 v[56:59], v[140:143], v[164:167], v[56:59]
	v_mfma_f32_16x16x32_bf16 v[40:43], v[140:143], v[194:197], v[40:43]
	v_mfma_f32_16x16x32_bf16 v[24:27], v[140:143], v[202:205], v[24:27]
	v_mfma_f32_16x16x32_bf16 v[8:11], v[140:143], v[210:213], v[8:11]
	s_setprio 0
	s_setprio 1
	v_mfma_f32_16x16x32_bf16 v[52:55], v[144:147], v[160:163], v[52:55]
	v_mfma_f32_16x16x32_bf16 v[36:39], v[144:147], v[190:193], v[36:39]
	v_mfma_f32_16x16x32_bf16 v[20:23], v[144:147], v[198:201], v[20:23]
	v_mfma_f32_16x16x32_bf16 v[4:7], v[144:147], v[206:209], v[4:7]
	v_mfma_f32_16x16x32_bf16 v[52:55], v[148:151], v[164:167], v[52:55]
	v_mfma_f32_16x16x32_bf16 v[36:39], v[148:151], v[194:197], v[36:39]
	v_mfma_f32_16x16x32_bf16 v[20:23], v[148:151], v[202:205], v[20:23]
	v_mfma_f32_16x16x32_bf16 v[4:7], v[148:151], v[210:213], v[4:7]
	v_mfma_f32_16x16x32_bf16 v[48:51], v[152:155], v[160:163], v[48:51]
	v_mfma_f32_16x16x32_bf16 v[32:35], v[152:155], v[190:193], v[32:35]
	v_mfma_f32_16x16x32_bf16 v[16:19], v[152:155], v[198:201], v[16:19]
	v_mfma_f32_16x16x32_bf16 v[0:3], v[152:155], v[206:209], v[0:3]
	v_mfma_f32_16x16x32_bf16 v[48:51], v[156:159], v[164:167], v[48:51]
	v_mfma_f32_16x16x32_bf16 v[32:35], v[156:159], v[194:197], v[32:35]
	v_mfma_f32_16x16x32_bf16 v[16:19], v[156:159], v[202:205], v[16:19]
	v_mfma_f32_16x16x32_bf16 v[0:3], v[156:159], v[210:213], v[0:3]
	s_setprio 0
	s_barrier
	s_add_i32 s57, s57, 2
	s_add_u32 s8, s8, 0x100
	s_addc_u32 s9, s9, 0
	s_add_u32 s55, s55, 0x100
	s_addc_u32 s56, s56, 0
	s_cmp_gt_u32 s57, 61
	s_cbranch_scc0 .LBB0_986
	s_and_b64 vcc, exec, s[12:13]
	s_cbranch_vccz .LBB0_989
	s_barrier
